# v15: v9 + up-GEMM relu epilogue: canonicalise+max pairs folded into one v_max (113 sites)
# baseline (speedup 1.0000x reference)
; DI u32x4 pk8(f32x4 a, f32x4 b) { u32x4 r; r.x = pk2(a[0], a[1]); r.y = pk2(a[2], a[3]); r.z = pk2(b[0], b[1]); r.w = pk2(b[2], b[3]); return r; }
; DI float sigm(float x) { return __builtin_amdgcn_rcpf(1.0f + __expf(-x)); }
;     DI void operator()(const Acc& acc, const pg8::Unit& u, int wr, int wc, int fr, int fq) const {
;     ...
;         for (int ai = 0; ai < 2; ++ai)
; #pragma unroll
;             for (int m = 0; m < 4; ++m) { const int row = row0 + ai * 128 + m * 16;
; #pragma unroll
;                 for (int bj = 0; bj < 2; ++bj) { f32x4 v0 = acc[ai][bj][m][0], v1 = acc[ai][bj][m][1];
; #pragma unroll
;                     for (int j = 0; j < 4; ++j) {
;                         if (ACT == 0) { const float a = fmaxf(v0[j], 0.f), b = fmaxf(v1[j], 0.f); v0[j] = a * a; v1[j] = b * b; }
;                         else { v0[j] = sigm(v0[j]); v1[j] = sigm(v1[j]); } }
;                     if (ACT == 0) __builtin_nontemporal_store(pk8(v0, v1), (u32x4*)(o + (size_t)row * ldc + c0 + bj * 128));
;                     else *(u32x4*)(o + (size_t)row * ldc + c0 + bj * 128) = pk8(v0, v1); } }
.LBB0_1370:
	s_lshl_b32 s4, s78, 8
	v_mov_b32_e32 v149, v139
	v_mov_b32_e32 v151, v138
	s_add_i32 s4, s4, s85
	s_lshl_b32 s0, s0, 8
	v_max_f32_e32 v120, 0, v120
	v_max_f32_e32 v121, 0, v121
	s_or_b32 s0, s0, s86
	v_add_u32_e32 v150, s4, v149
	v_max_f32_e32 v122, 0, v122
	v_max_f32_e32 v123, 0, v123
	v_lshl_add_u32 v152, v151, 3, s0
	v_ashrrev_i32_e32 v151, 31, v150
	v_max_f32_e32 v124, 0, v124
	v_max_f32_e32 v125, 0, v125
	v_pk_mul_f32 v[120:121], v[120:121], v[120:121]
	v_max_f32_e32 v126, 0, v126
	v_max_f32_e32 v127, 0, v127
	v_readlane_b32 s4, v237, 44
	v_pk_mul_f32 v[154:155], v[122:123], v[122:123]
	v_cvt_pk_bf16_f32 v122, v120, v121
	v_lshlrev_b64 v[120:121], 13, v[150:151]
	v_readlane_b32 s5, v237, 45
	v_ashrrev_i32_e32 v153, 31, v152
	v_pk_mul_f32 v[124:125], v[124:125], v[124:125]
	v_pk_mul_f32 v[126:127], v[126:127], v[126:127]
	v_lshl_add_u64 v[120:121], s[4:5], 0, v[120:121]
	v_max_f32_e32 v112, 0, v112
	v_max_f32_e32 v113, 0, v113
	v_cvt_pk_bf16_f32 v123, v154, v155
	v_cvt_pk_bf16_f32 v124, v124, v125
	v_cvt_pk_bf16_f32 v125, v126, v127
	v_lshl_add_u64 v[120:121], v[152:153], 1, v[120:121]
	global_store_dwordx4 v[120:121], v[122:125], off nt
	v_max_f32_e32 v116, 0, v116
	v_max_f32_e32 v117, 0, v117
	v_pk_mul_f32 v[122:123], v[112:113], v[112:113]
	v_max_f32_e32 v113, v114, v114
	v_max_f32_e32 v112, 0, v118
	v_max_f32_e32 v114, 0, v113
	v_max_f32_e32 v113, 0, v119
	v_max_f32_e32 v115, 0, v115
	v_pk_mul_f32 v[116:117], v[116:117], v[116:117]
	v_pk_mul_f32 v[118:119], v[112:113], v[112:113]
	v_pk_mul_f32 v[124:125], v[114:115], v[114:115]
	v_max_f32_e32 v104, 0, v104
	v_max_f32_e32 v105, 0, v105
	v_cvt_pk_bf16_f32 v112, v116, v117
	v_cvt_pk_bf16_f32 v113, v118, v119
	v_cvt_pk_bf16_f32 v114, v122, v123
	v_cvt_pk_bf16_f32 v115, v124, v125
	global_store_dwordx4 v[120:121], v[112:115], off offset:256 nt
	v_max_f32_e32 v108, 0, v108
	v_max_f32_e32 v109, 0, v109
	v_pk_mul_f32 v[112:113], v[104:105], v[104:105]
	v_max_f32_e32 v105, v106, v106
	v_max_f32_e32 v104, 0, v110
	v_max_f32_e32 v106, 0, v105
	v_max_f32_e32 v105, 0, v111
	v_max_f32_e32 v107, 0, v107
	v_pk_mul_f32 v[110:111], v[104:105], v[104:105]
	s_mov_b32 s0, 0x20000
	v_pk_mul_f32 v[108:109], v[108:109], v[108:109]
	v_pk_mul_f32 v[114:115], v[106:107], v[106:107]
	v_cvt_pk_bf16_f32 v105, v110, v111
	v_add_co_u32_e32 v110, vcc, s0, v120
	v_max_f32_e32 v96, 0, v96
	v_max_f32_e32 v97, 0, v97
	v_cvt_pk_bf16_f32 v104, v108, v109
	v_cvt_pk_bf16_f32 v106, v112, v113
	v_cvt_pk_bf16_f32 v107, v114, v115
	v_addc_co_u32_e32 v111, vcc, 0, v121, vcc
	global_store_dwordx4 v[110:111], v[104:107], off nt
	v_max_f32_e32 v100, 0, v100
	v_max_f32_e32 v101, 0, v101
	v_pk_mul_f32 v[104:105], v[96:97], v[96:97]
	v_max_f32_e32 v97, v98, v98
	v_max_f32_e32 v96, 0, v102
	v_max_f32_e32 v98, 0, v97
	v_max_f32_e32 v97, 0, v103
	v_max_f32_e32 v99, 0, v99
	s_mov_b64 s[4:5], 0x20000
	v_pk_mul_f32 v[100:101], v[100:101], v[100:101]
	v_pk_mul_f32 v[102:103], v[96:97], v[96:97]
	v_pk_mul_f32 v[106:107], v[98:99], v[98:99]
	v_max_f32_e32 v88, 0, v88
	v_max_f32_e32 v89, 0, v89
	v_lshl_add_u64 v[108:109], v[120:121], 0, s[4:5]
	v_cvt_pk_bf16_f32 v96, v100, v101
	v_cvt_pk_bf16_f32 v97, v102, v103
	v_cvt_pk_bf16_f32 v98, v104, v105
	v_cvt_pk_bf16_f32 v99, v106, v107
	global_store_dwordx4 v[108:109], v[96:99], off offset:256 nt
	v_max_f32_e32 v92, 0, v92
	v_max_f32_e32 v93, 0, v93
	v_pk_mul_f32 v[96:97], v[88:89], v[88:89]
	v_max_f32_e32 v89, v90, v90
	v_max_f32_e32 v88, 0, v94
	v_max_f32_e32 v90, 0, v89
	v_max_f32_e32 v89, 0, v95
	v_max_f32_e32 v91, 0, v91
	v_pk_mul_f32 v[94:95], v[88:89], v[88:89]
	s_mov_b32 s0, 0x40000
	v_pk_mul_f32 v[92:93], v[92:93], v[92:93]
	v_pk_mul_f32 v[98:99], v[90:91], v[90:91]
	v_cvt_pk_bf16_f32 v89, v94, v95
	v_add_co_u32_e32 v94, vcc, s0, v120
	v_max_f32_e32 v80, 0, v80
	v_max_f32_e32 v81, 0, v81
	v_cvt_pk_bf16_f32 v88, v92, v93
	v_cvt_pk_bf16_f32 v90, v96, v97
	v_cvt_pk_bf16_f32 v91, v98, v99
	v_addc_co_u32_e32 v95, vcc, 0, v121, vcc
	global_store_dwordx4 v[94:95], v[88:91], off nt
	v_max_f32_e32 v84, 0, v84
	v_max_f32_e32 v85, 0, v85
	v_pk_mul_f32 v[88:89], v[80:81], v[80:81]
	v_max_f32_e32 v81, v82, v82
	v_max_f32_e32 v80, 0, v86
	v_max_f32_e32 v82, 0, v81
	v_max_f32_e32 v81, 0, v87
	v_max_f32_e32 v83, 0, v83
	s_mov_b64 s[4:5], 0x40000
	v_pk_mul_f32 v[84:85], v[84:85], v[84:85]
	v_pk_mul_f32 v[86:87], v[80:81], v[80:81]
	v_pk_mul_f32 v[90:91], v[82:83], v[82:83]
	v_max_f32_e32 v72, 0, v72
	v_max_f32_e32 v73, 0, v73
	v_lshl_add_u64 v[92:93], v[120:121], 0, s[4:5]
	v_cvt_pk_bf16_f32 v80, v84, v85
	v_cvt_pk_bf16_f32 v81, v86, v87
	v_cvt_pk_bf16_f32 v82, v88, v89
	v_cvt_pk_bf16_f32 v83, v90, v91
	global_store_dwordx4 v[92:93], v[80:83], off offset:256 nt
	v_max_f32_e32 v76, 0, v76
	v_max_f32_e32 v77, 0, v77
	v_pk_mul_f32 v[80:81], v[72:73], v[72:73]
	v_max_f32_e32 v73, v74, v74
	v_max_f32_e32 v72, 0, v78
	v_max_f32_e32 v74, 0, v73
	v_max_f32_e32 v73, 0, v79
	v_max_f32_e32 v75, 0, v75
	v_pk_mul_f32 v[78:79], v[72:73], v[72:73]
	s_mov_b32 s0, 0x60000
	v_pk_mul_f32 v[76:77], v[76:77], v[76:77]
	v_pk_mul_f32 v[82:83], v[74:75], v[74:75]
	v_cvt_pk_bf16_f32 v73, v78, v79
	v_add_co_u32_e32 v78, vcc, s0, v120
	v_max_f32_e32 v64, 0, v64
	v_max_f32_e32 v65, 0, v65
	v_cvt_pk_bf16_f32 v72, v76, v77
	v_cvt_pk_bf16_f32 v74, v80, v81
	v_cvt_pk_bf16_f32 v75, v82, v83
	v_addc_co_u32_e32 v79, vcc, 0, v121, vcc
	global_store_dwordx4 v[78:79], v[72:75], off nt
	v_max_f32_e32 v68, 0, v68
	v_max_f32_e32 v69, 0, v69
	v_pk_mul_f32 v[72:73], v[64:65], v[64:65]
	v_max_f32_e32 v65, v66, v66
	v_max_f32_e32 v64, 0, v70
	v_max_f32_e32 v66, 0, v65
	v_max_f32_e32 v65, 0, v71
	v_max_f32_e32 v67, 0, v67
; DI u32x4 pk8(f32x4 a, f32x4 b) { u32x4 r; r.x = pk2(a[0], a[1]); r.y = pk2(a[2], a[3]); r.z = pk2(b[0], b[1]); r.w = pk2(b[2], b[3]); return r; }
; DI float sigm(float x) { return __builtin_amdgcn_rcpf(1.0f + __expf(-x)); }
;     DI void operator()(const Acc& acc, const pg8::Unit& u, int wr, int wc, int fr, int fq) const {
;     ...
;         for (int ai = 0; ai < 2; ++ai)
; #pragma unroll
;             for (int m = 0; m < 4; ++m) { const int row = row0 + ai * 128 + m * 16;
; #pragma unroll
;                 for (int bj = 0; bj < 2; ++bj) { f32x4 v0 = acc[ai][bj][m][0], v1 = acc[ai][bj][m][1];
; #pragma unroll
;                     for (int j = 0; j < 4; ++j) {
;                         if (ACT == 0) { const float a = fmaxf(v0[j], 0.f), b = fmaxf(v1[j], 0.f); v0[j] = a * a; v1[j] = b * b; }
;                         else { v0[j] = sigm(v0[j]); v1[j] = sigm(v1[j]); } }
;                     if (ACT == 0) __builtin_nontemporal_store(pk8(v0, v1), (u32x4*)(o + (size_t)row * ldc + c0 + bj * 128));
;                     else *(u32x4*)(o + (size_t)row * ldc + c0 + bj * 128) = pk8(v0, v1); } }
	s_mov_b64 s[4:5], 0x60000
	v_pk_mul_f32 v[68:69], v[68:69], v[68:69]
	v_pk_mul_f32 v[70:71], v[64:65], v[64:65]
	v_pk_mul_f32 v[74:75], v[66:67], v[66:67]
	v_max_f32_e32 v56, 0, v56
	v_max_f32_e32 v57, 0, v57
	v_lshl_add_u64 v[76:77], v[120:121], 0, s[4:5]
	v_cvt_pk_bf16_f32 v64, v68, v69
	v_cvt_pk_bf16_f32 v65, v70, v71
	v_cvt_pk_bf16_f32 v66, v72, v73
	v_cvt_pk_bf16_f32 v67, v74, v75
	global_store_dwordx4 v[76:77], v[64:67], off offset:256 nt
	v_max_f32_e32 v60, 0, v60
	v_max_f32_e32 v61, 0, v61
	v_pk_mul_f32 v[64:65], v[56:57], v[56:57]
	v_max_f32_e32 v57, v58, v58
	v_max_f32_e32 v56, 0, v62
	v_max_f32_e32 v58, 0, v57
	v_max_f32_e32 v57, 0, v63
	v_max_f32_e32 v59, 0, v59
	v_pk_mul_f32 v[62:63], v[56:57], v[56:57]
	s_mov_b32 s0, 0x100000
	v_pk_mul_f32 v[60:61], v[60:61], v[60:61]
	v_pk_mul_f32 v[66:67], v[58:59], v[58:59]
	v_cvt_pk_bf16_f32 v57, v62, v63
	v_add_co_u32_e32 v62, vcc, s0, v120
	v_max_f32_e32 v48, 0, v48
	v_max_f32_e32 v49, 0, v49
	v_cvt_pk_bf16_f32 v56, v60, v61
	v_cvt_pk_bf16_f32 v58, v64, v65
	v_cvt_pk_bf16_f32 v59, v66, v67
	v_addc_co_u32_e32 v63, vcc, 0, v121, vcc
	global_store_dwordx4 v[62:63], v[56:59], off nt
	v_max_f32_e32 v52, 0, v52
	v_max_f32_e32 v53, 0, v53
	v_pk_mul_f32 v[56:57], v[48:49], v[48:49]
	v_max_f32_e32 v49, v50, v50
	v_max_f32_e32 v48, 0, v54
	v_max_f32_e32 v50, 0, v49
	v_max_f32_e32 v49, 0, v55
	v_max_f32_e32 v51, 0, v51
	s_mov_b64 s[4:5], 0x100000
	v_pk_mul_f32 v[52:53], v[52:53], v[52:53]
	v_pk_mul_f32 v[54:55], v[48:49], v[48:49]
	v_pk_mul_f32 v[58:59], v[50:51], v[50:51]
	v_max_f32_e32 v40, 0, v40
	v_max_f32_e32 v41, 0, v41
	v_lshl_add_u64 v[60:61], v[120:121], 0, s[4:5]
	v_cvt_pk_bf16_f32 v48, v52, v53
	v_cvt_pk_bf16_f32 v49, v54, v55
	v_cvt_pk_bf16_f32 v50, v56, v57
	v_cvt_pk_bf16_f32 v51, v58, v59
	global_store_dwordx4 v[60:61], v[48:51], off offset:256 nt
	v_max_f32_e32 v44, 0, v44
	v_max_f32_e32 v45, 0, v45
	v_pk_mul_f32 v[48:49], v[40:41], v[40:41]
	v_max_f32_e32 v41, v42, v42
	v_max_f32_e32 v40, 0, v46
	v_max_f32_e32 v42, 0, v41
	v_max_f32_e32 v41, 0, v47
	v_max_f32_e32 v43, 0, v43
	v_pk_mul_f32 v[46:47], v[40:41], v[40:41]
	s_mov_b32 s0, 0x120000
	v_pk_mul_f32 v[44:45], v[44:45], v[44:45]
	v_pk_mul_f32 v[50:51], v[42:43], v[42:43]
	v_cvt_pk_bf16_f32 v41, v46, v47
	v_add_co_u32_e32 v46, vcc, s0, v120
	v_max_f32_e32 v32, 0, v32
	v_max_f32_e32 v33, 0, v33
	v_cvt_pk_bf16_f32 v40, v44, v45
	v_cvt_pk_bf16_f32 v42, v48, v49
	v_cvt_pk_bf16_f32 v43, v50, v51
	v_addc_co_u32_e32 v47, vcc, 0, v121, vcc
	global_store_dwordx4 v[46:47], v[40:43], off nt
	v_max_f32_e32 v36, 0, v36
	v_max_f32_e32 v37, 0, v37
	v_pk_mul_f32 v[40:41], v[32:33], v[32:33]
	v_max_f32_e32 v33, v34, v34
	v_max_f32_e32 v32, 0, v38
	v_max_f32_e32 v34, 0, v33
	v_max_f32_e32 v33, 0, v39
	v_max_f32_e32 v35, 0, v35
	s_mov_b64 s[4:5], 0x120000
	v_pk_mul_f32 v[36:37], v[36:37], v[36:37]
	v_pk_mul_f32 v[38:39], v[32:33], v[32:33]
	v_pk_mul_f32 v[42:43], v[34:35], v[34:35]
	v_max_f32_e32 v24, 0, v24
	v_max_f32_e32 v25, 0, v25
	v_lshl_add_u64 v[44:45], v[120:121], 0, s[4:5]
	v_cvt_pk_bf16_f32 v32, v36, v37
	v_cvt_pk_bf16_f32 v33, v38, v39
	v_cvt_pk_bf16_f32 v34, v40, v41
	v_cvt_pk_bf16_f32 v35, v42, v43
	global_store_dwordx4 v[44:45], v[32:35], off offset:256 nt
	v_max_f32_e32 v28, 0, v28
	v_max_f32_e32 v29, 0, v29
	v_pk_mul_f32 v[32:33], v[24:25], v[24:25]
	v_max_f32_e32 v25, v26, v26
	v_max_f32_e32 v24, 0, v30
	v_max_f32_e32 v26, 0, v25
	v_max_f32_e32 v25, 0, v31
	v_max_f32_e32 v27, 0, v27
	v_pk_mul_f32 v[30:31], v[24:25], v[24:25]
	s_mov_b32 s0, 0x140000
	v_pk_mul_f32 v[28:29], v[28:29], v[28:29]
	v_pk_mul_f32 v[34:35], v[26:27], v[26:27]
	v_cvt_pk_bf16_f32 v25, v30, v31
	v_add_co_u32_e32 v30, vcc, s0, v120
	v_max_f32_e32 v16, 0, v16
	v_max_f32_e32 v17, 0, v17
	v_cvt_pk_bf16_f32 v24, v28, v29
	v_cvt_pk_bf16_f32 v26, v32, v33
	v_cvt_pk_bf16_f32 v27, v34, v35
	v_addc_co_u32_e32 v31, vcc, 0, v121, vcc
	global_store_dwordx4 v[30:31], v[24:27], off nt
	v_max_f32_e32 v20, 0, v20
	v_max_f32_e32 v21, 0, v21
	v_pk_mul_f32 v[24:25], v[16:17], v[16:17]
	v_max_f32_e32 v17, v18, v18
	v_max_f32_e32 v16, 0, v22
	v_max_f32_e32 v18, 0, v17
	v_max_f32_e32 v17, 0, v23
	v_max_f32_e32 v19, 0, v19
	s_mov_b64 s[4:5], 0x140000
	v_pk_mul_f32 v[20:21], v[20:21], v[20:21]
	v_pk_mul_f32 v[22:23], v[16:17], v[16:17]
	v_pk_mul_f32 v[26:27], v[18:19], v[18:19]
	v_max_f32_e32 v8, 0, v8
	v_max_f32_e32 v9, 0, v9
	v_lshl_add_u64 v[28:29], v[120:121], 0, s[4:5]
	v_cvt_pk_bf16_f32 v16, v20, v21
	v_cvt_pk_bf16_f32 v17, v22, v23
	v_cvt_pk_bf16_f32 v18, v24, v25
	v_cvt_pk_bf16_f32 v19, v26, v27
	global_store_dwordx4 v[28:29], v[16:19], off offset:256 nt
	v_max_f32_e32 v12, 0, v12
	v_max_f32_e32 v13, 0, v13
	v_pk_mul_f32 v[16:17], v[8:9], v[8:9]
	v_max_f32_e32 v9, v10, v10
	v_max_f32_e32 v8, 0, v14
	v_max_f32_e32 v10, 0, v9
	v_max_f32_e32 v9, 0, v15
	v_max_f32_e32 v11, 0, v11
	v_pk_mul_f32 v[14:15], v[8:9], v[8:9]
	s_mov_b32 s0, 0x160000
	v_pk_mul_f32 v[12:13], v[12:13], v[12:13]
	v_pk_mul_f32 v[18:19], v[10:11], v[10:11]
	v_cvt_pk_bf16_f32 v9, v14, v15
	v_add_co_u32_e32 v14, vcc, s0, v120
	v_max_f32_e32 v0, 0, v0
	v_max_f32_e32 v1, 0, v1
	v_cvt_pk_bf16_f32 v8, v12, v13
	v_cvt_pk_bf16_f32 v10, v16, v17
	v_cvt_pk_bf16_f32 v11, v18, v19
	v_addc_co_u32_e32 v15, vcc, 0, v121, vcc
	global_store_dwordx4 v[14:15], v[8:11], off nt
	v_max_f32_e32 v4, 0, v4
	v_max_f32_e32 v5, 0, v5
	v_pk_mul_f32 v[8:9], v[0:1], v[0:1]
	v_max_f32_e32 v1, v2, v2
	v_max_f32_e32 v0, 0, v6
	v_max_f32_e32 v2, 0, v1
	v_max_f32_e32 v1, 0, v7
	v_max_f32_e32 v3, 0, v3
	s_mov_b64 s[4:5], 0x160000
	v_pk_mul_f32 v[4:5], v[4:5], v[4:5]
	v_pk_mul_f32 v[6:7], v[0:1], v[0:1]
	v_pk_mul_f32 v[10:11], v[2:3], v[2:3]
	v_lshl_add_u64 v[12:13], v[120:121], 0, s[4:5]
	v_cvt_pk_bf16_f32 v0, v4, v5
	v_cvt_pk_bf16_f32 v1, v6, v7
	v_cvt_pk_bf16_f32 v2, v8, v9
	v_cvt_pk_bf16_f32 v3, v10, v11
	s_and_b64 vcc, exec, s[38:39]
	s_mov_b32 s0, s82
	s_mov_b32 s78, s83
	s_mov_b64 s[44:45], s[18:19]
	s_mov_b64 s[36:37], s[16:17]
	global_store_dwordx4 v[12:13], v[0:3], off offset:256 nt
	s_cbranch_vccnz .LBB0_1380
